# next-layer weight conversion: all gate/up items (2816 instead of 2432) taken by the spare-round workgroups of the gate/up GEMM phase; NSA unit epilogue: one batch of line-touch loads before its serial
# speedup vs baseline: 1.0289x; 1.0018x over previous
.LBB0_153:
	s_or_b64 exec, exec, s[8:9]
	s_cmpk_lt_i32 s31, 0x200
	s_cselect_b64 s[0:1], -1, 0
	v_writelane_b32 v253, s0, 10
	v_mov_b32_e32 v1, 0
	v_mov_b32_e32 v204, 0x3727c5ac
	v_writelane_b32 v253, s1, 11
	s_ashr_i32 s0, s31, 31
	v_writelane_b32 v253, s0, 12
	s_lshr_b32 s0, s0, 29
	s_add_i32 s1, s31, s0
	s_ashr_i32 s0, s1, 3
	s_and_b32 s1, s1, -8
	s_sub_i32 s1, s31, s1
	v_readlane_b32 s14, v253, 0
	s_lshl_b32 s8, s1, 6
	s_ashr_i32 s9, s14, 31
	s_add_u32 s10, s4, 0x10200
	v_readlane_b32 s15, v253, 1
	v_writelane_b32 v253, s9, 13
	s_addc_u32 s11, s5, 0
	v_writelane_b32 v253, s10, 14
	v_mov_b32_e32 v205, 0x260
	v_mov_b32_e32 v252, 1
	v_writelane_b32 v253, s11, 15
	s_add_u32 s10, s4, 0x10400
	s_addc_u32 s11, s5, 0
	v_writelane_b32 v253, s10, 16
	v_mbcnt_hi_u32_b32 v147, -1, v18
	v_mov_b32_e32 v208, 0x7f
	v_writelane_b32 v253, s11, 17
	s_add_u32 s10, s4, 0x10500
	s_addc_u32 s11, s5, 0
	v_writelane_b32 v253, s10, 18
	v_mov_b32_e32 v148, 0xf149f2ca
	v_mov_b32_e32 v209, 0x7149f2ca
	v_writelane_b32 v253, s11, 19
	s_add_u32 s10, s4, 0x10600
	s_addc_u32 s11, s5, 0
	v_writelane_b32 v253, s10, 20
	v_mov_b64_e32 v[150:151], 0x100
	v_mov_b64_e32 v[152:153], 0xff
	v_writelane_b32 v253, s11, 21
	s_add_u32 s10, s4, 0x10700
	s_addc_u32 s11, s5, 0
	v_writelane_b32 v253, s10, 22
	v_mov_b64_e32 v[250:251], 0x580
	v_mov_b64_e32 v[206:207], 0x57f
	v_writelane_b32 v253, s11, 23
	s_add_u32 s10, s4, 0x10800
	s_addc_u32 s11, s5, 0
	v_writelane_b32 v253, s10, 24
	s_movk_i32 s24, 0x7f
	s_movk_i32 s26, 0x80
	v_writelane_b32 v253, s11, 25
	s_add_u32 s10, s4, 0x10900
	s_addc_u32 s11, s5, 0
	v_writelane_b32 v253, s10, 26
	s_movk_i32 s27, 0xff
	s_movk_i32 s83, 0x1000
	v_writelane_b32 v253, s11, 27
	s_add_u32 s10, s4, 0x10a00
	s_addc_u32 s11, s5, 0
	v_writelane_b32 v253, s10, 28
	s_mov_b32 s29, 0xf149f2ca
	s_mov_b32 s30, 0xefa18f08
	v_writelane_b32 v253, s11, 29
	s_add_u32 s10, s4, 0x10b00
	s_addc_u32 s11, s5, 0
	v_writelane_b32 v253, s10, 30
	s_movk_i32 s28, 0x1600
	s_mov_b64 s[34:35], 0x80
	v_writelane_b32 v253, s11, 31
	s_add_u32 s10, s4, 0x10c00
	s_addc_u32 s11, s5, 0
	v_writelane_b32 v253, s10, 32
	s_mov_b32 s36, 0x3e38aa3b
	s_mov_b64 s[84:85], 0xc00
	v_writelane_b32 v253, s11, 33
	s_add_u32 s10, s4, 0x10d00
	s_addc_u32 s11, s5, 0
	v_writelane_b32 v253, s10, 34
	s_mov_b64 s[86:87], 0xe00
	s_nop 0
	v_writelane_b32 v253, s11, 35
	s_add_u32 s10, s4, 0x10e00
	s_addc_u32 s11, s5, 0
	v_writelane_b32 v253, s10, 36
	s_nop 1
	v_writelane_b32 v253, s11, 37
	s_add_u32 s10, s4, 0x10f00
	s_addc_u32 s11, s5, 0
	v_writelane_b32 v253, s10, 38
	s_nop 1
	v_writelane_b32 v253, s11, 39
	s_add_u32 s10, s4, 0x11000
	s_addc_u32 s11, s5, 0
	v_writelane_b32 v253, s10, 40
	s_nop 1
	v_writelane_b32 v253, s11, 41
	s_add_u32 s10, s4, 0x11100
	s_addc_u32 s11, s5, 0
	v_writelane_b32 v253, s10, 42
	s_nop 1
	v_writelane_b32 v253, s11, 43
	s_add_u32 s10, s4, 0x11200
	s_addc_u32 s11, s5, 0
	v_writelane_b32 v253, s10, 44
	s_nop 1
	v_writelane_b32 v253, s11, 45
	s_add_u32 s10, s4, 0x11300
	s_addc_u32 s11, s5, 0
	v_writelane_b32 v253, s10, 46
	s_cmp_eq_u32 s2, 15
	s_nop 0
	v_writelane_b32 v253, s11, 47
	s_cselect_b64 s[10:11], -1, 0
	v_writelane_b32 v253, s10, 48
	s_cmp_eq_u32 s2, 14
	s_nop 0
	v_writelane_b32 v253, s11, 49
	s_cselect_b64 s[10:11], -1, 0
	v_writelane_b32 v253, s10, 50
	s_cmp_eq_u32 s2, 13
	s_nop 0
	v_writelane_b32 v253, s11, 51
	s_cselect_b64 s[10:11], -1, 0
	v_writelane_b32 v253, s10, 52
	s_cmp_eq_u32 s2, 12
	s_nop 0
	v_writelane_b32 v253, s11, 53
	s_cselect_b64 s[10:11], -1, 0
	v_writelane_b32 v253, s10, 54
	s_cmp_eq_u32 s2, 11
	s_nop 0
	v_writelane_b32 v253, s11, 55
	s_cselect_b64 s[10:11], -1, 0
	v_writelane_b32 v253, s10, 56
	s_cmp_eq_u32 s2, 10
	s_nop 0
	v_writelane_b32 v253, s11, 57
	s_cselect_b64 s[10:11], -1, 0
	v_writelane_b32 v253, s10, 58
	s_cmp_eq_u32 s2, 9
	s_nop 0
	v_writelane_b32 v253, s11, 59
	s_cselect_b64 s[10:11], -1, 0
	v_writelane_b32 v253, s10, 60
	s_cmp_eq_u32 s2, 8
	s_nop 0
	v_writelane_b32 v253, s11, 61
	s_cselect_b64 s[10:11], -1, 0
	v_writelane_b32 v253, s10, 62
	s_cmp_eq_u32 s2, 7
	s_nop 0
	v_writelane_b32 v253, s11, 63
	s_cselect_b64 s[10:11], -1, 0
	v_writelane_b32 v254, s10, 0
	s_cmp_eq_u32 s2, 6
	v_readlane_b32 s13, v253, 7
	v_writelane_b32 v254, s11, 1
	s_cselect_b64 s[10:11], -1, 0
	v_writelane_b32 v254, s10, 2
	s_cmp_eq_u32 s2, 5
	s_nop 0
	v_writelane_b32 v254, s11, 3
	s_cselect_b64 s[10:11], -1, 0
	v_writelane_b32 v254, s10, 4
	s_cmp_eq_u32 s2, 4
	s_nop 0
	v_writelane_b32 v254, s11, 5
	s_cselect_b64 s[10:11], -1, 0
	v_writelane_b32 v254, s10, 6
	s_cmp_eq_u32 s2, 3
	s_nop 0
	v_writelane_b32 v254, s11, 7
	s_cselect_b64 s[10:11], -1, 0
	v_writelane_b32 v254, s10, 8
	s_cmp_eq_u32 s2, 2
	s_nop 0
	v_writelane_b32 v254, s11, 9
	s_cselect_b64 s[10:11], -1, 0
	v_writelane_b32 v254, s10, 10
	s_cmp_eq_u32 s2, 1
	s_nop 0
	v_writelane_b32 v254, s11, 11
	s_cselect_b64 s[10:11], -1, 0
	v_writelane_b32 v254, s10, 12
	s_cmp_eq_u32 s2, 0
	s_nop 0
	v_writelane_b32 v254, s11, 13
	s_cselect_b64 s[10:11], -1, 0
	s_lshl_b32 s2, s3, 2
	s_add_u32 s2, s6, s2
	s_addc_u32 s3, s7, 0
	v_writelane_b32 v254, s10, 14
	s_add_u32 s6, s2, 0x1400
	s_addc_u32 s7, s3, 0
	v_writelane_b32 v254, s11, 15
	v_writelane_b32 v254, s6, 16
	s_add_u32 s2, s2, 0x2400
	s_addc_u32 s3, s3, 0
	v_writelane_b32 v254, s7, 17
	v_writelane_b32 v254, s2, 18
	s_nop 1
	v_writelane_b32 v254, s3, 19
	s_add_u32 s2, s4, 0x13400
	s_addc_u32 s3, s5, 0
	v_writelane_b32 v254, s2, 20
	s_nop 1
	v_writelane_b32 v254, s3, 21
	s_add_u32 s2, s4, 0x13500
	s_addc_u32 s3, s5, 0
	v_writelane_b32 v254, s2, 22
	s_cmpk_lt_i32 s31, 0x500
	s_nop 0
	v_writelane_b32 v254, s3, 23
	s_cselect_b64 s[2:3], -1, 0
	v_writelane_b32 v254, s2, 24
	s_cmpk_lg_i32 s14, 0x100
	s_nop 0
	v_writelane_b32 v254, s3, 25
	s_cselect_b64 s[2:3], -1, 0
	v_writelane_b32 v254, s2, 26
	s_lshl_b32 s4, s31, 6
	s_and_b32 s5, s4, 64
	v_writelane_b32 v254, s3, 27
	s_and_b32 s2, s31, 7
	s_lshl_b32 s3, s2, 6
	v_writelane_b32 v254, s3, 28
	s_and_b32 s3, s3, 0x180
	s_or_b32 s3, s3, s5
	s_ashr_i32 s5, s31, 3
	v_writelane_b32 v254, s3, 29
	s_lshl_b32 s2, s2, 4
	s_and_b32 s3, s5, 15
	s_or_b32 s2, s2, s3
	s_and_b32 s3, s31, 0xffffff80
	s_or_b32 s2, s2, s3
	s_load_dword s3, s[40:41], 0xa8
	v_writelane_b32 v254, s2, 30
	s_mul_i32 s2, s15, s14
	s_waitcnt lgkmcnt(0)
	s_mul_i32 s2, s2, s3
	v_writelane_b32 v254, s2, 31
	s_and_b32 s2, s4, 0x1c0
	v_writelane_b32 v254, s2, 32
	s_sub_i32 s2, 63, s5
	v_writelane_b32 v254, s5, 33
	s_cmpk_lt_i32 s31, 0x100
	v_writelane_b32 v254, s2, 34
	s_cselect_b64 s[2:3], -1, 0
	s_lshl_b32 s6, s1, 5
	v_writelane_b32 v254, s2, 35
	s_cmpk_lt_i32 s31, 0x580
	s_nop 0
	v_writelane_b32 v254, s3, 36
	s_cselect_b64 s[2:3], -1, 0
	v_writelane_b32 v254, s2, 37
	s_cmpk_gt_i32 s31, 0x7f
	s_cselect_b64 s[4:5], -1, 0
	v_writelane_b32 v254, s3, 38
	s_add_i32 s2, s13, 0xfffffc00
	s_cmpk_eq_i32 s14, 0x100
	s_cselect_b64 s[18:19], -1, 0
	v_writelane_b32 v254, s2, 39
	s_and_b64 s[2:3], s[18:19], exec
	s_cselect_b32 s15, 0xb00, 0
	s_cmp_lt_i32 s1, 0
	s_mul_i32 s2, s1, 0x41
	s_mul_i32 s3, s1, 33
	s_cselect_b32 s2, s2, s8
	s_cselect_b32 s3, s3, s6
	s_movk_i32 s6, 0xb1
	s_cselect_b32 s6, s6, 0xb0
	s_add_i32 s2, s2, s0
	s_ashr_i32 s7, s2, 31
	s_lshr_b32 s7, s7, 25
	s_add_i32 s7, s2, s7
	s_and_b32 s8, s7, 0xff80
	s_sub_i32 s2, s2, s8
	s_bfe_i32 s8, s2, 0x80000
	s_bfe_u32 s8, s8, 0x3000c
	s_add_i32 s8, s2, s8
	s_and_b32 s9, s8, 0xf8
	s_add_i32 s3, s3, s0
	s_sub_i32 s2, s2, s9
	s_ashr_i32 s9, s3, 31
	s_lshr_b32 s9, s9, 26
	s_mul_i32 s1, s1, s6
	s_add_i32 s9, s3, s9
	s_add_i32 s1, s1, s0
	s_and_b32 s10, s9, 0xffc0
	s_mul_hi_i32 s0, s1, 0x2e8ba2e9
	s_sub_i32 s3, s3, s10
	s_lshr_b32 s6, s0, 31
	s_ashr_i32 s0, s0, 6
	s_bfe_i32 s10, s3, 0x80000
	s_add_i32 s6, s0, s6
	s_bfe_u32 s10, s10, 0x3000c
	s_mul_i32 s0, s6, 0x160
	s_add_i32 s10, s3, s10
	s_sub_i32 s0, s1, s0
	s_and_b32 s11, s10, 0xf8
	s_bfe_u32 s1, s0, 0x3001c
	s_sub_i32 s3, s3, s11
	s_add_i32 s11, s0, s1
	s_and_b32 s1, s11, 0xfff8
	s_sub_i32 s12, s0, s1
	s_ashr_i32 s0, s7, 7
	s_bfe_i32 s1, s8, 0x80000
	s_lshl_b32 s0, s0, 3
	s_sext_i32_i16 s1, s1
	s_sext_i32_i8 s2, s2
	s_add_i32 s20, s0, s2
	s_ashr_i32 s0, s1, 3
	v_writelane_b32 v254, s0, 40
	s_lshr_b32 s0, s1, 3
	s_bfe_i64 s[0:1], s[0:1], 0x100000
	s_lshl_b64 s[0:1], s[0:1], 20
	v_writelane_b32 v254, s0, 41
	s_ashr_i32 s21, s20, 31
	s_nop 0
	v_writelane_b32 v254, s1, 42
	s_ashr_i32 s0, s9, 6
	s_bfe_i32 s1, s10, 0x80000
	s_lshl_b32 s0, s0, 3
	s_sext_i32_i16 s2, s1
	s_sext_i32_i8 s1, s3
	s_add_i32 s8, s0, s1
	s_lshl_b32 s0, s6, 3
	s_sext_i32_i16 s1, s11
	s_sext_i32_i16 s3, s12
	s_add_i32 s6, s0, s3
	s_ashr_i32 s0, s1, 3
	v_writelane_b32 v254, s0, 43
	s_lshr_b32 s0, s1, 3
	s_bfe_i64 s[0:1], s[0:1], 0x100000
	s_lshl_b64 s[0:1], s[0:1], 20
	v_writelane_b32 v254, s0, 44
	s_ashr_i32 s7, s6, 31
	s_ashr_i32 s9, s8, 31
	v_writelane_b32 v254, s1, 45
	s_ashr_i32 s0, s2, 3
	v_writelane_b32 v254, s0, 46
	s_lshr_b32 s0, s2, 3
	s_bfe_i64 s[0:1], s[0:1], 0x100000
	s_lshl_b64 s[0:1], s[0:1], 20
	v_writelane_b32 v254, s0, 47
	s_add_i32 s2, s15, s13
	s_addk_i32 s2, 0xe8f8
	v_writelane_b32 v254, s1, 48
	v_writelane_b32 v254, s18, 49
	s_and_b64 s[0:1], s[4:5], s[18:19]
	s_xor_b64 s[0:1], s[0:1], -1
	v_writelane_b32 v254, s19, 50
	v_writelane_b32 v254, s15, 51
	v_writelane_b32 v254, s2, 52
	v_writelane_b32 v254, s0, 53
	s_movk_i32 s3, 0x200
	s_nop 0
	v_writelane_b32 v254, s1, 54
	s_lshl_b32 s0, s31, 10
	v_writelane_b32 v254, s0, 55
	s_add_i32 s0, s0, 0xfffe0000
	v_writelane_b32 v254, s0, 56
	s_lshl_b32 s0, s14, 9
	v_writelane_b32 v254, s0, 57
	s_add_i32 s0, 0, 0x20200
	v_writelane_b32 v254, s0, 58
	s_add_i32 s0, 0, 0x20204
	v_writelane_b32 v254, s0, 59
	s_mov_b32 s0, s20
	v_writelane_b32 v254, s0, 60
	s_movk_i32 s31, 0x3ff
	s_nop 0
	v_writelane_b32 v254, s1, 61
	s_lshl_b64 s[0:1], s[20:21], 20
	v_writelane_b32 v254, s0, 62
	s_nop 1
	v_writelane_b32 v254, s1, 63
	s_mov_b32 s0, s6
	v_writelane_b32 v255, s0, 0
	s_nop 1
	v_writelane_b32 v255, s1, 1
	s_lshl_b64 s[0:1], s[6:7], 20
	v_writelane_b32 v255, s0, 2
	s_nop 1
	v_writelane_b32 v255, s1, 3
	s_mov_b32 s0, s8
	v_writelane_b32 v255, s0, 4
	s_nop 1
	v_writelane_b32 v255, s1, 5
	s_lshl_b64 s[0:1], s[8:9], 20
	v_writelane_b32 v255, s0, 6
	s_nop 1
	v_writelane_b32 v255, s1, 7
	s_mov_b64 s[0:1], 0x203c00
	v_writelane_b32 v255, s0, 8
	s_nop 1
	v_writelane_b32 v255, s1, 9
	s_mov_b64 s[0:1], 0
	v_writelane_b32 v255, s0, 10
	s_nop 1
	v_writelane_b32 v255, s1, 11
	s_mov_b64 s[0:1], 0
	v_writelane_b32 v255, s0, 12
	s_nop 1
	v_writelane_b32 v255, s1, 13
	s_mov_b64 s[0:1], 0
	v_writelane_b32 v255, s0, 14
	s_nop 1
	v_writelane_b32 v255, s1, 15
	s_mov_b32 s0, s17
	v_writelane_b32 v255, s0, 16
	s_nop 1
	v_writelane_b32 v255, s1, 17
	s_branch .LBB0_156

.LBB0_350:
	v_readlane_b32 s4, v255, 18
	v_lshlrev_b32_e32 v0, 1, v138
	v_readlane_b32 s5, v255, 19
	v_lshl_add_u64 v[40:41], v[128:129], 0, v[0:1]
	v_lshl_add_u64 v[38:39], v[130:131], 0, v[0:1]
	v_lshl_add_u64 v[2:3], s[4:5], 0, v[120:121]
	v_lshlrev_b32_e32 v0, 1, v118
	v_lshl_add_u64 v[2:3], v[2:3], 0, v[0:1]
	v_add_co_u32_e32 v2, vcc, 0x1000, v2
	s_waitcnt vmcnt(0) lgkmcnt(0)
	s_nop 0
	v_addc_co_u32_e32 v3, vcc, 0, v3, vcc
	s_barrier
	global_load_dword v80, v[116:117], off
	global_load_dword v81, v[116:117], off offset:1024
	global_load_dword v82, v[104:105], off
	global_load_dword v83, v[108:109], off
	global_load_dword v84, v[110:111], off
	global_load_dword v85, v[106:107], off
	v_lshlrev_b64 v[90:91], 11, v[114:115]
	v_lshl_add_u64 v[90:91], v[40:41], 0, v[90:91]
	global_load_dword v86, v[90:91], off
	v_lshlrev_b64 v[90:91], 11, v[102:103]
	v_lshl_add_u64 v[90:91], v[40:41], 0, v[90:91]
	global_load_dword v87, v[90:91], off
	v_lshl_add_u64 v[90:91], s[4:5], 0, v[112:113]
	v_lshl_add_u64 v[90:91], v[90:91], 0, v[0:1]
	v_add_co_u32_e32 v90, vcc, s83, v90
	s_nop 1
	v_addc_co_u32_e32 v91, vcc, 0, v91, vcc
	global_load_dword v88, v[90:91], off offset:3586
	global_load_dword v2, v[2:3], off offset:3586
	s_nop 0
	global_load_dwordx4 v[10:13], v[116:117], off offset:2048
	global_load_dwordx4 v[14:17], v[116:117], off offset:3072
	s_waitcnt vmcnt(2)
	v_lshlrev_b32_e32 v3, 16, v2
	v_mul_f32_e32 v3, 0xbfb8aa3b, v3
	v_exp_f32_e32 v3, v3
	v_and_b32_e32 v2, 0xffff0000, v2
	v_mul_f32_e32 v2, 0xbfb8aa3b, v2
	v_exp_f32_e32 v2, v2
	v_add_f32_e32 v3, 1.0, v3
	v_div_scale_f32 v4, s[0:1], v3, v3, 1.0
	v_rcp_f32_e32 v5, v4
	v_add_f32_e32 v55, 1.0, v2
	ds_bpermute_b32 v2, v119, v144
	v_fma_f32 v6, -v4, v5, 1.0
	v_fmac_f32_e32 v5, v6, v5
	v_div_scale_f32 v6, vcc, 1.0, v3, 1.0
	v_mul_f32_e32 v7, v6, v5
	v_fma_f32 v8, -v4, v7, v6
	v_fmac_f32_e32 v7, v8, v5
	v_fma_f32 v4, -v4, v7, v6
	v_div_fmas_f32 v4, v4, v5, v7
	s_waitcnt lgkmcnt(0)
	v_add_f32_e32 v2, v144, v2
	v_div_fixup_f32 v3, v4, v3, 1.0
	ds_bpermute_b32 v4, v137, v2
	s_waitcnt lgkmcnt(0)
	v_add_f32_e32 v2, v2, v4
	v_div_scale_f32 v4, s[0:1], v2, v2, 1.0
	v_rcp_f32_e32 v5, v4
	v_cmp_lt_f32_e64 s[6:7], 0, v2
	v_fma_f32 v6, -v4, v5, 1.0
	v_fmac_f32_e32 v5, v6, v5
	v_div_scale_f32 v6, vcc, 1.0, v2, 1.0
	v_mul_f32_e32 v7, v6, v5
	v_fma_f32 v8, -v4, v7, v6
	v_fmac_f32_e32 v7, v8, v5
	v_fma_f32 v4, -v4, v7, v6
	v_div_fmas_f32 v4, v4, v5, v7
	v_div_fixup_f32 v2, v4, v2, 1.0
	v_cndmask_b32_e64 v2, 0, v2, s[6:7]
	v_mul_f32_e32 v54, v3, v2
	global_load_dwordx4 v[2:5], v[116:117], off
	global_load_dwordx4 v[6:9], v[116:117], off offset:1024
	s_waitcnt vmcnt(3)
	v_pk_fma_f32 v[10:11], v[42:43], v[54:55], v[10:11] op_sel_hi:[1,0,1]
	v_pk_fma_f32 v[12:13], v[44:45], v[54:55], v[12:13] op_sel_hi:[1,0,1]
	s_waitcnt vmcnt(2)
	v_pk_fma_f32 v[16:17], v[52:53], v[54:55], v[16:17] op_sel_hi:[1,0,1]
	v_pk_fma_f32 v[14:15], v[50:51], v[54:55], v[14:15] op_sel_hi:[1,0,1]
	s_waitcnt vmcnt(1)
	v_pk_fma_f32 v[2:3], v[34:35], v[54:55], v[2:3] op_sel_hi:[1,0,1]
	v_div_scale_f32 v34, s[0:1], v55, v55, 1.0
	v_rcp_f32_e32 v35, v34
	v_pk_fma_f32 v[4:5], v[36:37], v[54:55], v[4:5] op_sel_hi:[1,0,1]
	s_waitcnt vmcnt(0)
	v_pk_fma_f32 v[8:9], v[48:49], v[54:55], v[8:9] op_sel_hi:[1,0,1]
	v_pk_fma_f32 v[6:7], v[46:47], v[54:55], v[6:7] op_sel_hi:[1,0,1]
	v_fma_f32 v36, -v34, v35, 1.0
	v_fmac_f32_e32 v35, v36, v35
	v_div_scale_f32 v36, vcc, 1.0, v55, 1.0
	v_mul_f32_e32 v37, v36, v35
	v_fma_f32 v42, -v34, v37, v36
	v_fmac_f32_e32 v37, v42, v35
	v_fma_f32 v34, -v34, v37, v36
	v_div_fmas_f32 v34, v34, v35, v37
	v_add_u32_e32 v35, v214, v213
	ds_write_b128 v35, v[2:5] offset:16384
	ds_write_b128 v35, v[6:9] offset:16448
	ds_write_b128 v35, v[10:13] offset:16512
	ds_write_b128 v35, v[14:17] offset:16576
	s_waitcnt lgkmcnt(0)
	v_add_u32_e32 v36, v214, v215
	ds_read_b128 v[14:17], v36 offset:16384
	ds_read_b128 v[10:13], v36 offset:16400
	ds_read_b128 v[6:9], v36 offset:16416
	ds_read_b128 v[2:5], v36 offset:16432
	s_waitcnt lgkmcnt(0)
	v_lshlrev_b64 v[42:43], 11, v[114:115]
	v_lshl_add_u64 v[46:47], v[40:41], 0, v[42:43]
	global_load_dwordx4 v[42:45], v[46:47], off offset:16
	s_nop 0
	global_load_dwordx4 v[46:49], v[46:47], off
	v_div_fixup_f32 v34, v34, v55, 1.0
	s_waitcnt vmcnt(0)
	v_lshlrev_b32_e32 v50, 16, v46
	v_and_b32_e32 v51, 0xffff0000, v46
	v_lshlrev_b32_e32 v46, 16, v47
	v_and_b32_e32 v47, 0xffff0000, v47
	s_waitcnt lgkmcnt(3)
	v_pk_fma_f32 v[16:17], v[34:35], v[46:47], v[16:17] op_sel_hi:[0,1,1]
	v_lshlrev_b32_e32 v46, 16, v48
	v_and_b32_e32 v47, 0xffff0000, v48
	s_waitcnt lgkmcnt(2)
	v_pk_fma_f32 v[10:11], v[34:35], v[46:47], v[10:11] op_sel_hi:[0,1,1]
	v_lshlrev_b32_e32 v46, 16, v49
	v_and_b32_e32 v47, 0xffff0000, v49
	v_pk_fma_f32 v[12:13], v[34:35], v[46:47], v[12:13] op_sel_hi:[0,1,1]
	v_lshlrev_b32_e32 v46, 16, v42
	v_and_b32_e32 v47, 0xffff0000, v42
	v_lshlrev_b32_e32 v42, 16, v43
	v_and_b32_e32 v43, 0xffff0000, v43
	s_waitcnt lgkmcnt(1)
	v_pk_fma_f32 v[8:9], v[34:35], v[42:43], v[8:9] op_sel_hi:[0,1,1]
	v_lshlrev_b32_e32 v42, 16, v44
	v_and_b32_e32 v43, 0xffff0000, v44
	s_waitcnt lgkmcnt(0)
	v_pk_fma_f32 v[42:43], v[34:35], v[42:43], v[2:3] op_sel_hi:[0,1,1]
	v_lshlrev_b32_e32 v2, 16, v45
	v_and_b32_e32 v3, 0xffff0000, v45
	v_pk_fma_f32 v[14:15], v[34:35], v[50:51], v[14:15] op_sel_hi:[0,1,1]
	v_pk_fma_f32 v[44:45], v[34:35], v[2:3], v[4:5] op_sel_hi:[0,1,1]
	v_lshlrev_b64 v[2:3], 12, v[114:115]
	v_pk_fma_f32 v[6:7], v[34:35], v[46:47], v[6:7] op_sel_hi:[0,1,1]
	v_lshl_add_u64 v[46:47], v[38:39], 0, v[2:3]
	v_cvt_pk_bf16_f32 v2, v14, v15
	v_cvt_pk_bf16_f32 v3, v16, v17
	v_cvt_pk_bf16_f32 v4, v10, v11
	v_cvt_pk_bf16_f32 v5, v12, v13
	v_cvt_pk_bf16_f32 v6, v6, v7
	v_cvt_pk_bf16_f32 v7, v8, v9
	v_cvt_pk_bf16_f32 v8, v42, v43
	v_cvt_pk_bf16_f32 v9, v44, v45
	global_store_dwordx4 v[46:47], v[2:5], off
	global_store_dwordx4 v[46:47], v[6:9], off offset:16
	global_load_dwordx4 v[14:17], v[104:105], off
	v_lshl_add_u64 v[2:3], s[4:5], 0, v[112:113]
	v_lshl_add_u64 v[2:3], v[2:3], 0, v[0:1]
	v_add_co_u32_e32 v2, vcc, s83, v2
	global_load_dwordx4 v[10:13], v[108:109], off
	s_nop 0
	v_addc_co_u32_e32 v3, vcc, 0, v3, vcc
	global_load_dword v0, v[2:3], off offset:3586
	s_waitcnt vmcnt(0)
	v_lshlrev_b32_e32 v2, 16, v0
	v_mul_f32_e32 v2, 0xbfb8aa3b, v2
	v_exp_f32_e32 v2, v2
	v_and_b32_e32 v0, 0xffff0000, v0
	v_mul_f32_e32 v0, 0xbfb8aa3b, v0
	v_exp_f32_e32 v0, v0
	v_add_f32_e32 v2, 1.0, v2
	v_div_scale_f32 v3, s[0:1], v2, v2, 1.0
	v_rcp_f32_e32 v4, v3
	v_add_f32_e32 v34, 1.0, v0
	ds_bpermute_b32 v0, v119, v145
	v_fma_f32 v5, -v3, v4, 1.0
	v_fmac_f32_e32 v4, v5, v4
	v_div_scale_f32 v5, vcc, 1.0, v2, 1.0
	v_mul_f32_e32 v6, v5, v4
	v_fma_f32 v7, -v3, v6, v5
	v_fmac_f32_e32 v6, v7, v4
	v_fma_f32 v3, -v3, v6, v5
	v_div_fmas_f32 v3, v3, v4, v6
	s_waitcnt lgkmcnt(0)
	v_add_f32_e32 v0, v145, v0
	v_div_fixup_f32 v2, v3, v2, 1.0
	ds_bpermute_b32 v3, v137, v0
	s_waitcnt lgkmcnt(0)
	v_add_f32_e32 v0, v0, v3
	v_div_scale_f32 v3, s[0:1], v0, v0, 1.0
	v_rcp_f32_e32 v4, v3
	v_cmp_lt_f32_e64 s[6:7], 0, v0
	v_fma_f32 v5, -v3, v4, 1.0
	v_fmac_f32_e32 v4, v5, v4
	v_div_scale_f32 v5, vcc, 1.0, v0, 1.0
	v_mul_f32_e32 v6, v5, v4
	v_fma_f32 v7, -v3, v6, v5
	v_fmac_f32_e32 v6, v7, v4
	v_fma_f32 v3, -v3, v6, v5
	v_div_fmas_f32 v3, v3, v4, v6
	v_div_fixup_f32 v0, v3, v0, 1.0
	v_cndmask_b32_e64 v0, 0, v0, s[6:7]
	v_mul_f32_e32 v0, v2, v0
	global_load_dwordx4 v[2:5], v[110:111], off
	global_load_dwordx4 v[6:9], v[106:107], off
	v_pk_fma_f32 v[16:17], v[20:21], v[0:1], v[16:17] op_sel_hi:[1,0,1]
	v_pk_fma_f32 v[14:15], v[18:19], v[0:1], v[14:15] op_sel_hi:[1,0,1]
	v_pk_fma_f32 v[12:13], v[24:25], v[0:1], v[12:13] op_sel_hi:[1,0,1]
	v_pk_fma_f32 v[10:11], v[22:23], v[0:1], v[10:11] op_sel_hi:[1,0,1]
	s_waitcnt vmcnt(1)
	v_pk_fma_f32 v[4:5], v[32:33], v[0:1], v[4:5] op_sel_hi:[1,0,1]
	v_pk_fma_f32 v[2:3], v[30:31], v[0:1], v[2:3] op_sel_hi:[1,0,1]
	s_waitcnt vmcnt(0)
	v_pk_fma_f32 v[8:9], v[28:29], v[0:1], v[8:9] op_sel_hi:[1,0,1]
	v_pk_fma_f32 v[6:7], v[26:27], v[0:1], v[6:7] op_sel_hi:[1,0,1]
	v_div_scale_f32 v0, s[0:1], v34, v34, 1.0
	v_rcp_f32_e32 v18, v0
	ds_write_b128 v35, v[2:5] offset:16384
	ds_write_b128 v35, v[6:9] offset:16448
	ds_write_b128 v35, v[10:13] offset:16512
	ds_write_b128 v35, v[14:17] offset:16576
	s_waitcnt lgkmcnt(0)
	v_fma_f32 v19, -v0, v18, 1.0
	v_fmac_f32_e32 v18, v19, v18
	v_div_scale_f32 v19, vcc, 1.0, v34, 1.0
	v_mul_f32_e32 v20, v19, v18
	v_fma_f32 v21, -v0, v20, v19
	v_fmac_f32_e32 v20, v21, v18
	v_fma_f32 v0, -v0, v20, v19
	v_div_fmas_f32 v0, v0, v18, v20
	ds_read_b128 v[14:17], v36 offset:16384
	ds_read_b128 v[10:13], v36 offset:16400
	ds_read_b128 v[6:9], v36 offset:16416
	ds_read_b128 v[2:5], v36 offset:16432
	s_waitcnt lgkmcnt(0)
	v_lshlrev_b64 v[18:19], 11, v[102:103]
	v_lshl_add_u64 v[22:23], v[40:41], 0, v[18:19]
	global_load_dwordx4 v[18:21], v[22:23], off offset:16
	s_nop 0
	global_load_dwordx4 v[22:25], v[22:23], off
	v_div_fixup_f32 v0, v0, v34, 1.0
	v_readlane_b32 s0, v253, 0
	s_add_i32 s33, s33, s0
	s_cmpk_gt_i32 s33, 0x1ff
	v_readlane_b32 s1, v253, 1
	s_waitcnt vmcnt(0)
	v_lshlrev_b32_e32 v26, 16, v22
	v_and_b32_e32 v27, 0xffff0000, v22
	v_lshlrev_b32_e32 v22, 16, v23
	v_and_b32_e32 v23, 0xffff0000, v23
	s_waitcnt lgkmcnt(3)
	v_pk_fma_f32 v[16:17], v[0:1], v[22:23], v[16:17] op_sel_hi:[0,1,1]
	v_lshlrev_b32_e32 v22, 16, v24
	v_and_b32_e32 v23, 0xffff0000, v24
	s_waitcnt lgkmcnt(2)
	v_pk_fma_f32 v[10:11], v[0:1], v[22:23], v[10:11] op_sel_hi:[0,1,1]
	v_lshlrev_b32_e32 v22, 16, v25
	v_and_b32_e32 v23, 0xffff0000, v25
	v_pk_fma_f32 v[12:13], v[0:1], v[22:23], v[12:13] op_sel_hi:[0,1,1]
	v_lshlrev_b32_e32 v22, 16, v18
	v_and_b32_e32 v23, 0xffff0000, v18
	v_lshlrev_b32_e32 v18, 16, v19
	v_and_b32_e32 v19, 0xffff0000, v19
	s_waitcnt lgkmcnt(1)
	v_pk_fma_f32 v[8:9], v[0:1], v[18:19], v[8:9] op_sel_hi:[0,1,1]
	v_lshlrev_b32_e32 v18, 16, v20
	v_and_b32_e32 v19, 0xffff0000, v20
	s_waitcnt lgkmcnt(0)
	v_pk_fma_f32 v[18:19], v[0:1], v[18:19], v[2:3] op_sel_hi:[0,1,1]
	v_lshlrev_b32_e32 v2, 16, v21
	v_and_b32_e32 v3, 0xffff0000, v21
	v_pk_fma_f32 v[14:15], v[0:1], v[26:27], v[14:15] op_sel_hi:[0,1,1]
	v_pk_fma_f32 v[20:21], v[0:1], v[2:3], v[4:5] op_sel_hi:[0,1,1]
	v_lshlrev_b64 v[2:3], 12, v[102:103]
	v_pk_fma_f32 v[6:7], v[0:1], v[22:23], v[6:7] op_sel_hi:[0,1,1]
	v_lshl_add_u64 v[22:23], v[38:39], 0, v[2:3]
	v_cvt_pk_bf16_f32 v2, v14, v15
	v_cvt_pk_bf16_f32 v3, v16, v17
	v_cvt_pk_bf16_f32 v4, v10, v11
	v_cvt_pk_bf16_f32 v5, v12, v13
	v_cvt_pk_bf16_f32 v6, v6, v7
	v_cvt_pk_bf16_f32 v7, v8, v9
	v_cvt_pk_bf16_f32 v8, v18, v19
	v_cvt_pk_bf16_f32 v9, v20, v21
	global_store_dwordx4 v[22:23], v[2:5], off
	global_store_dwordx4 v[22:23], v[6:9], off offset:16
	s_cbranch_scc1 .LBB0_451

.LBB0_611:
	v_readlane_b32 s0, v255, 16
	v_readlane_b32 s1, v255, 17
	s_cmp_eq_u32 s0, 3
	s_cselect_b64 s[4:5], -1, 0
	s_and_b64 s[0:1], s[8:9], exec
	v_readlane_b32 s6, v254, 53
	s_mov_b32 s0, 0x1900000
	v_readlane_b32 s7, v254, 54
	s_cselect_b32 s0, 0x1be00000, s0
	s_or_b64 s[4:5], s[4:5], s[6:7]
	s_and_b64 vcc, exec, s[4:5]
	s_cbranch_vccnz .LBB0_659
	s_mov_b64 s[6:7], s[40:41]
	v_mov_b32_e32 v2, v146
	v_readlane_b32 s2, v254, 39
	v_readfirstlane_b32 s1, v2
	s_ashr_i32 s1, s1, 6
	s_add_i32 s2, s2, s1
	s_cmpk_gt_i32 s2, 0xaff
	s_cbranch_scc1 .LBB0_659
	s_load_dwordx2 s[4:5], s[6:7], 0x98
	s_lshl_b32 s10, s1, 14
	v_lshlrev_b32_e32 v0, 2, v2
	s_add_i32 s10, s10, 0
	v_and_b32_e32 v41, 0x7c, v0
	s_waitcnt lgkmcnt(0)
	s_add_u32 s4, s4, s0
	v_lshlrev_b32_e32 v0, 4, v2
	s_addc_u32 s5, s5, 0
	v_and_b32_e32 v0, 0x70, v0
	v_lshl_add_u64 v[34:35], s[4:5], 0, v[0:1]
	s_lshl_b32 s4, s1, 7
	v_readlane_b32 s5, v254, 55
	v_bfe_u32 v43, v2, 3, 3
	s_add_i32 s4, s4, s5
	v_bfe_u32 v0, v2, 5, 1
	v_add_u32_e32 v49, s4, v43
	v_readlane_b32 s4, v254, 56
	v_and_b32_e32 v40, 63, v2
	v_and_b32_e32 v42, 32, v2
	v_and_b32_e32 v44, 4, v43
	v_and_b32_e32 v45, 7, v2
	v_lshl_add_u32 v46, v41, 7, s10
	v_or_b32_e32 v47, 6, v0
	v_lshl_add_u32 v48, v43, 7, s10
	v_or_b32_e32 v50, 4, v0
	v_or_b32_e32 v51, 2, v0
	v_add_u32_e32 v52, s4, v43
	s_branch .LBB0_615
.LBB0_614:
	s_waitcnt lgkmcnt(0)
	s_add_i32 s4, s2, 0x400
	v_add_u32_e32 v49, 0x20000, v49
	v_add_u32_e32 v52, 0x20000, v52
	s_cmpk_lt_i32 s2, 0x700
	s_mov_b32 s2, s4
	s_cbranch_scc0 .LBB0_659
